# v8 + bf16 K-loops: MFMAs within each 8-MFMA group ordered so consecutive MFMAs share a source operand (bit-identical accumulation order per accumulator)
# speedup vs baseline: 1.1186x; 1.1186x over previous
; #define PG8_STAGE(bufoff, gbase, voff) do { _Pragma("unroll") for (int _i = 0; _i < 2; ++_i) \
;         __builtin_amdgcn_global_load_lds((const unsigned*)((const char*)(gbase) + (voff)[_i]), (LAS unsigned*)(lds + (bufoff) + ldsw + _i * 8192), 16, 0, 0); } while (0)
; #define PG8_LDA(dst, b, h) do { _Pragma("unroll") for (int m = 0; m < 4; ++m) _Pragma("unroll") for (int k = 0; k < 2; ++k) dst[m][k] = *(const LAS bf16x8*)(lds + PG8_SA(b, h) + aoff + m * 2048 + k * KOFF); } while (0)
; #define PG8_LDB(dst, b, h) do { _Pragma("unroll") for (int n = 0; n < 2; ++n) _Pragma("unroll") for (int k = 0; k < 2; ++k) dst[n][k] = *(const LAS bf16x8*)(lds + PG8_SB(b, h) + boff + n * 2048 + k * KOFF); } while (0)
; #define PG8_WAIT_V(n) asm volatile("s_waitcnt vmcnt(" #n ")" ::: "memory")
; #define PG8_WAIT_L(n) asm volatile("s_waitcnt lgkmcnt(" #n ")" ::: "memory")
; #define PG8_BAR __builtin_amdgcn_s_barrier()
; #define PG8_SCHED __builtin_amdgcn_sched_barrier(0)
; template <class Epi, bool ALIGN_EPI = true, bool FP8 = false>
; __device__ __forceinline__ void gemm_phase(LAS unsigned char* lds, const Gemm g, const StaticOrder& S, const Epi& E, const int wid) {
;     ...
;             const char* a1 = cA + (size_t)(t + 1) * kstep;
;             const char* a2 = last ? nA : cA + (size_t)(t + 2) * kstep; const char* b2 = last ? nB : cB + (size_t)(t + 2) * kstep;
;             const char* a3 = a2 + kstep; const char* b3 = b2 + kstep;
;             PG8_LDB(B0, 0, 0); PG8_LDB(B1, 0, 1); PG8_SCHED; PG8_LDA(At, 0, 0); PG8_STAGE(PG8_SA(1, 1), a1 + hstep, voffA);
;             PG8_WAIT_V(8); PG8_WAIT_L(0); PG8_BAR; PG8_MMA(0, 0, At, B0); PG8_MMA(0, 1, At, B1); PG8_BAR; PG8_SCHED;
;             PG8_LDA(At, 0, 1); PG8_STAGE(PG8_SB(0, 0), b2, voffB); PG8_STAGE(PG8_SB(0, 1), b2 + hstep, voffB); PG8_STAGE(PG8_SA(0, 0), a2, voffA);
;             PG8_WAIT_V(8); PG8_WAIT_L(0); PG8_BAR; PG8_MMA(1, 0, At, B0); PG8_MMA(1, 1, At, B1); PG8_BAR; PG8_SCHED;
.LBB0_506:
	ds_read_b128 v[146:149], v137
	ds_read_b128 v[154:157], v137 offset:1024
	ds_read_b128 v[158:161], v137 offset:2048
	ds_read_b128 v[162:165], v137 offset:3072
	ds_read_b128 v[166:169], v152
	ds_read_b128 v[170:173], v152 offset:1024
	ds_read_b128 v[174:177], v152 offset:2048
	ds_read_b128 v[178:181], v152 offset:3072
	s_add_i32 s52, s34, 2
	s_add_u32 s35, s30, 0xfff80080
	s_addc_u32 s36, s31, -1
	s_cmp_eq_u32 s39, s34
	s_cselect_b32 s34, s38, s42
	s_cselect_b32 s37, s3, s36
	s_cselect_b32 s36, s23, s35
	s_cselect_b32 s35, s25, s43
	v_lshl_add_u64 v[214:215], s[30:31], 0, v[140:141]
	s_add_i32 m0, s75, 0xc000
	ds_read_b128 v[182:185], v153
	ds_read_b128 v[186:189], v153 offset:1024
	ds_read_b128 v[190:193], v153 offset:2048
	ds_read_b128 v[194:197], v153 offset:3072
	ds_read_b128 v[198:201], v153 offset:4096
	ds_read_b128 v[202:205], v153 offset:5120
	ds_read_b128 v[206:209], v153 offset:6144
	ds_read_b128 v[210:213], v153 offset:7168
	global_load_lds_dwordx4 v[214:215], off
	v_lshl_add_u64 v[214:215], s[30:31], 0, v[142:143]
	s_add_i32 m0, s75, 0xe000
	s_nop 0
	global_load_lds_dwordx4 v[214:215], off
	s_setprio 1
	s_waitcnt vmcnt(8) lgkmcnt(0)
	s_barrier
	v_mfma_f32_16x16x32_bf16 v[124:127], v[146:149], v[182:185], v[124:127]
	v_mfma_f32_16x16x32_bf16 v[120:123], v[158:161], v[182:185], v[120:123]
	v_mfma_f32_16x16x32_bf16 v[104:107], v[158:161], v[190:193], v[104:107]
	v_mfma_f32_16x16x32_bf16 v[108:111], v[146:149], v[190:193], v[108:111]
	v_mfma_f32_16x16x32_bf16 v[92:95], v[146:149], v[198:201], v[92:95]
	v_mfma_f32_16x16x32_bf16 v[88:91], v[158:161], v[198:201], v[88:91]
	v_mfma_f32_16x16x32_bf16 v[72:75], v[158:161], v[206:209], v[72:75]
	v_mfma_f32_16x16x32_bf16 v[76:79], v[146:149], v[206:209], v[76:79]
	v_mfma_f32_16x16x32_bf16 v[124:127], v[154:157], v[186:189], v[124:127]
	v_mfma_f32_16x16x32_bf16 v[120:123], v[162:165], v[186:189], v[120:123]
	v_mfma_f32_16x16x32_bf16 v[104:107], v[162:165], v[194:197], v[104:107]
	v_mfma_f32_16x16x32_bf16 v[108:111], v[154:157], v[194:197], v[108:111]
	v_mfma_f32_16x16x32_bf16 v[92:95], v[154:157], v[202:205], v[92:95]
	v_mfma_f32_16x16x32_bf16 v[88:91], v[162:165], v[202:205], v[88:91]
	v_mfma_f32_16x16x32_bf16 v[72:75], v[162:165], v[210:213], v[72:75]
	v_mfma_f32_16x16x32_bf16 v[76:79], v[154:157], v[210:213], v[76:79]
	v_mfma_f32_16x16x32_bf16 v[116:119], v[166:169], v[182:185], v[116:119]
	v_mfma_f32_16x16x32_bf16 v[112:115], v[174:177], v[182:185], v[112:115]
	v_mfma_f32_16x16x32_bf16 v[96:99], v[174:177], v[190:193], v[96:99]
	v_mfma_f32_16x16x32_bf16 v[100:103], v[166:169], v[190:193], v[100:103]
	v_mfma_f32_16x16x32_bf16 v[84:87], v[166:169], v[198:201], v[84:87]
	v_mfma_f32_16x16x32_bf16 v[80:83], v[174:177], v[198:201], v[80:83]
	v_mfma_f32_16x16x32_bf16 v[64:67], v[174:177], v[206:209], v[64:67]
	v_mfma_f32_16x16x32_bf16 v[68:71], v[166:169], v[206:209], v[68:71]
	v_mfma_f32_16x16x32_bf16 v[116:119], v[170:173], v[186:189], v[116:119]
	v_mfma_f32_16x16x32_bf16 v[112:115], v[178:181], v[186:189], v[112:115]
	v_mfma_f32_16x16x32_bf16 v[96:99], v[178:181], v[194:197], v[96:99]
	v_mfma_f32_16x16x32_bf16 v[100:103], v[170:173], v[194:197], v[100:103]
	v_mfma_f32_16x16x32_bf16 v[84:87], v[170:173], v[202:205], v[84:87]
	v_mfma_f32_16x16x32_bf16 v[80:83], v[178:181], v[202:205], v[80:83]
	v_mfma_f32_16x16x32_bf16 v[64:67], v[178:181], v[210:213], v[64:67]
	v_mfma_f32_16x16x32_bf16 v[68:71], v[170:173], v[210:213], v[68:71]
	s_barrier
	s_setprio 0
	s_add_i32 s54, s86, s48
	v_lshl_add_u64 v[214:215], s[34:35], 0, v[132:133]
	s_mov_b32 m0, s54
	ds_read_b128 v[182:185], v153 offset:16384
	ds_read_b128 v[186:189], v153 offset:17408
	ds_read_b128 v[190:193], v153 offset:18432
	ds_read_b128 v[194:197], v153 offset:19456
	ds_read_b128 v[198:201], v153 offset:20480
	ds_read_b128 v[202:205], v153 offset:21504
	ds_read_b128 v[206:209], v153 offset:22528
	ds_read_b128 v[210:213], v153 offset:23552
	global_load_lds_dwordx4 v[214:215], off
	s_add_i32 m0, s54, 0x2000
	s_add_u32 s64, s34, 0x80000
	v_lshl_add_u64 v[216:217], s[34:35], 0, v[128:129]
	s_addc_u32 s65, s35, 0
	s_add_i32 s54, s87, s48
	global_load_lds_dwordx4 v[216:217], off
	v_lshl_add_u64 v[218:219], s[64:65], 0, v[132:133]
	s_mov_b32 m0, s54
	v_lshl_add_u64 v[220:221], s[36:37], 0, v[130:131]
	global_load_lds_dwordx4 v[218:219], off
	v_lshl_add_u64 v[218:219], s[64:65], 0, v[128:129]
	s_add_i32 m0, s54, 0x2000
	s_nop 0
	global_load_lds_dwordx4 v[218:219], off
	v_lshl_add_u64 v[218:219], s[36:37], 0, v[134:135]
	s_mov_b32 m0, s75
	s_nop 0
	global_load_lds_dwordx4 v[218:219], off
	s_mov_b32 m0, s76
	s_nop 0
	global_load_lds_dwordx4 v[220:221], off
	s_setprio 1
	s_waitcnt vmcnt(8) lgkmcnt(0)
	s_barrier
; #define PG8_STAGE(bufoff, gbase, voff) do { _Pragma("unroll") for (int _i = 0; _i < 2; ++_i) \
;         __builtin_amdgcn_global_load_lds((const unsigned*)((const char*)(gbase) + (voff)[_i]), (LAS unsigned*)(lds + (bufoff) + ldsw + _i * 8192), 16, 0, 0); } while (0)
; #define PG8_LDA(dst, b, h) do { _Pragma("unroll") for (int m = 0; m < 4; ++m) _Pragma("unroll") for (int k = 0; k < 2; ++k) dst[m][k] = *(const LAS bf16x8*)(lds + PG8_SA(b, h) + aoff + m * 2048 + k * KOFF); } while (0)
; #define PG8_LDB(dst, b, h) do { _Pragma("unroll") for (int n = 0; n < 2; ++n) _Pragma("unroll") for (int k = 0; k < 2; ++k) dst[n][k] = *(const LAS bf16x8*)(lds + PG8_SB(b, h) + boff + n * 2048 + k * KOFF); } while (0)
; #define PG8_WAIT_V(n) asm volatile("s_waitcnt vmcnt(" #n ")" ::: "memory")
; #define PG8_WAIT_L(n) asm volatile("s_waitcnt lgkmcnt(" #n ")" ::: "memory")
; #define PG8_BAR __builtin_amdgcn_s_barrier()
; #define PG8_SCHED __builtin_amdgcn_sched_barrier(0)
; template <class Epi, bool ALIGN_EPI = true, bool FP8 = false>
; __device__ __forceinline__ void gemm_phase(LAS unsigned char* lds, const Gemm g, const StaticOrder& S, const Epi& E, const int wid) {
;     ...
;             PG8_WAIT_V(8); PG8_WAIT_L(0); PG8_BAR; PG8_MMA(1, 0, At, B0); PG8_MMA(1, 1, At, B1); PG8_BAR; PG8_SCHED;
;             PG8_LDB(B0, 1, 0); PG8_LDB(B1, 1, 1); PG8_SCHED; PG8_LDA(At, 1, 0); PG8_STAGE(PG8_SA(0, 1), a2 + hstep, voffA);
;             PG8_WAIT_V(8); PG8_WAIT_L(0); PG8_BAR; PG8_MMA(0, 0, At, B0); PG8_MMA(0, 1, At, B1); PG8_BAR; PG8_SCHED;
	v_mfma_f32_16x16x32_bf16 v[60:63], v[146:149], v[182:185], v[60:63]
	v_mfma_f32_16x16x32_bf16 v[56:59], v[158:161], v[182:185], v[56:59]
	v_mfma_f32_16x16x32_bf16 v[40:43], v[158:161], v[190:193], v[40:43]
	v_mfma_f32_16x16x32_bf16 v[44:47], v[146:149], v[190:193], v[44:47]
	v_mfma_f32_16x16x32_bf16 v[28:31], v[146:149], v[198:201], v[28:31]
	v_mfma_f32_16x16x32_bf16 v[24:27], v[158:161], v[198:201], v[24:27]
	v_mfma_f32_16x16x32_bf16 v[8:11], v[158:161], v[206:209], v[8:11]
	v_mfma_f32_16x16x32_bf16 v[12:15], v[146:149], v[206:209], v[12:15]
	v_mfma_f32_16x16x32_bf16 v[60:63], v[154:157], v[186:189], v[60:63]
	v_mfma_f32_16x16x32_bf16 v[56:59], v[162:165], v[186:189], v[56:59]
	v_mfma_f32_16x16x32_bf16 v[40:43], v[162:165], v[194:197], v[40:43]
	v_mfma_f32_16x16x32_bf16 v[44:47], v[154:157], v[194:197], v[44:47]
	v_mfma_f32_16x16x32_bf16 v[28:31], v[154:157], v[202:205], v[28:31]
	v_mfma_f32_16x16x32_bf16 v[24:27], v[162:165], v[202:205], v[24:27]
	v_mfma_f32_16x16x32_bf16 v[8:11], v[162:165], v[210:213], v[8:11]
	v_mfma_f32_16x16x32_bf16 v[12:15], v[154:157], v[210:213], v[12:15]
	v_mfma_f32_16x16x32_bf16 v[52:55], v[166:169], v[182:185], v[52:55]
	v_mfma_f32_16x16x32_bf16 v[48:51], v[174:177], v[182:185], v[48:51]
	v_mfma_f32_16x16x32_bf16 v[32:35], v[174:177], v[190:193], v[32:35]
	v_mfma_f32_16x16x32_bf16 v[36:39], v[166:169], v[190:193], v[36:39]
	v_mfma_f32_16x16x32_bf16 v[20:23], v[166:169], v[198:201], v[20:23]
	v_mfma_f32_16x16x32_bf16 v[16:19], v[174:177], v[198:201], v[16:19]
	v_mfma_f32_16x16x32_bf16 v[0:3], v[174:177], v[206:209], v[0:3]
	v_mfma_f32_16x16x32_bf16 v[4:7], v[166:169], v[206:209], v[4:7]
	v_mfma_f32_16x16x32_bf16 v[52:55], v[170:173], v[186:189], v[52:55]
	v_mfma_f32_16x16x32_bf16 v[48:51], v[178:181], v[186:189], v[48:51]
	v_mfma_f32_16x16x32_bf16 v[32:35], v[178:181], v[194:197], v[32:35]
	v_mfma_f32_16x16x32_bf16 v[36:39], v[170:173], v[194:197], v[36:39]
	v_mfma_f32_16x16x32_bf16 v[20:23], v[170:173], v[202:205], v[20:23]
	v_mfma_f32_16x16x32_bf16 v[16:19], v[178:181], v[202:205], v[16:19]
	v_mfma_f32_16x16x32_bf16 v[0:3], v[178:181], v[210:213], v[0:3]
	v_mfma_f32_16x16x32_bf16 v[4:7], v[170:173], v[210:213], v[4:7]
	s_barrier
	s_setprio 0
	s_add_i32 s54, 0, 0x18000
	s_add_i32 s64, 0, 0x1c000
	v_add_u32_e32 v162, s54, v150
	v_add_u32_e32 v178, s64, v150
	ds_read_b128 v[146:149], v162
	ds_read_b128 v[154:157], v162 offset:1024
	ds_read_b128 v[158:161], v162 offset:2048
	ds_read_b128 v[162:165], v162 offset:3072
	ds_read_b128 v[166:169], v178
	ds_read_b128 v[170:173], v178 offset:1024
	ds_read_b128 v[174:177], v178 offset:2048
	ds_read_b128 v[178:181], v178 offset:3072
	s_add_u32 s36, s36, 0x80000
	s_addc_u32 s37, s37, 0
	s_mov_b32 m0, s77
	v_lshl_add_u64 v[222:223], s[36:37], 0, v[134:135]
	ds_read_b128 v[182:185], v153 offset:32768
	ds_read_b128 v[186:189], v153 offset:33792
	ds_read_b128 v[190:193], v153 offset:34816
	ds_read_b128 v[194:197], v153 offset:35840
	ds_read_b128 v[198:201], v153 offset:36864
	ds_read_b128 v[202:205], v153 offset:37888
	ds_read_b128 v[206:209], v153 offset:38912
	ds_read_b128 v[210:213], v153 offset:39936
	global_load_lds_dwordx4 v[222:223], off
	v_lshl_add_u64 v[222:223], s[36:37], 0, v[130:131]
	s_mov_b32 m0, s78
	s_nop 0
	global_load_lds_dwordx4 v[222:223], off
	s_setprio 1
	s_waitcnt vmcnt(8) lgkmcnt(0)
	s_barrier
	v_mfma_f32_16x16x32_bf16 v[124:127], v[146:149], v[182:185], v[124:127]
	v_mfma_f32_16x16x32_bf16 v[120:123], v[158:161], v[182:185], v[120:123]
	v_mfma_f32_16x16x32_bf16 v[104:107], v[158:161], v[190:193], v[104:107]
	v_mfma_f32_16x16x32_bf16 v[108:111], v[146:149], v[190:193], v[108:111]
	v_mfma_f32_16x16x32_bf16 v[92:95], v[146:149], v[198:201], v[92:95]
	v_mfma_f32_16x16x32_bf16 v[88:91], v[158:161], v[198:201], v[88:91]
	v_mfma_f32_16x16x32_bf16 v[72:75], v[158:161], v[206:209], v[72:75]
	v_mfma_f32_16x16x32_bf16 v[76:79], v[146:149], v[206:209], v[76:79]
	v_mfma_f32_16x16x32_bf16 v[124:127], v[154:157], v[186:189], v[124:127]
	v_mfma_f32_16x16x32_bf16 v[120:123], v[162:165], v[186:189], v[120:123]
	v_mfma_f32_16x16x32_bf16 v[104:107], v[162:165], v[194:197], v[104:107]
	v_mfma_f32_16x16x32_bf16 v[108:111], v[154:157], v[194:197], v[108:111]
	v_mfma_f32_16x16x32_bf16 v[92:95], v[154:157], v[202:205], v[92:95]
	v_mfma_f32_16x16x32_bf16 v[88:91], v[162:165], v[202:205], v[88:91]
	v_mfma_f32_16x16x32_bf16 v[72:75], v[162:165], v[210:213], v[72:75]
	v_mfma_f32_16x16x32_bf16 v[76:79], v[154:157], v[210:213], v[76:79]
	v_mfma_f32_16x16x32_bf16 v[116:119], v[166:169], v[182:185], v[116:119]
	v_mfma_f32_16x16x32_bf16 v[112:115], v[174:177], v[182:185], v[112:115]
	v_mfma_f32_16x16x32_bf16 v[96:99], v[174:177], v[190:193], v[96:99]
	v_mfma_f32_16x16x32_bf16 v[100:103], v[166:169], v[190:193], v[100:103]
	v_mfma_f32_16x16x32_bf16 v[84:87], v[166:169], v[198:201], v[84:87]
	v_mfma_f32_16x16x32_bf16 v[80:83], v[174:177], v[198:201], v[80:83]
	v_mfma_f32_16x16x32_bf16 v[64:67], v[174:177], v[206:209], v[64:67]
	v_mfma_f32_16x16x32_bf16 v[68:71], v[166:169], v[206:209], v[68:71]
	v_mfma_f32_16x16x32_bf16 v[116:119], v[170:173], v[186:189], v[116:119]
	v_mfma_f32_16x16x32_bf16 v[112:115], v[178:181], v[186:189], v[112:115]
	v_mfma_f32_16x16x32_bf16 v[96:99], v[178:181], v[194:197], v[96:99]
	v_mfma_f32_16x16x32_bf16 v[100:103], v[170:173], v[194:197], v[100:103]
	v_mfma_f32_16x16x32_bf16 v[84:87], v[170:173], v[202:205], v[84:87]
	v_mfma_f32_16x16x32_bf16 v[80:83], v[178:181], v[202:205], v[80:83]
	v_mfma_f32_16x16x32_bf16 v[64:67], v[178:181], v[210:213], v[64:67]
	v_mfma_f32_16x16x32_bf16 v[68:71], v[170:173], v[210:213], v[68:71]
	s_barrier
; #define PG8_STAGE(bufoff, gbase, voff) do { _Pragma("unroll") for (int _i = 0; _i < 2; ++_i) \
;         __builtin_amdgcn_global_load_lds((const unsigned*)((const char*)(gbase) + (voff)[_i]), (LAS unsigned*)(lds + (bufoff) + ldsw + _i * 8192), 16, 0, 0); } while (0)
; #define PG8_LDA(dst, b, h) do { _Pragma("unroll") for (int m = 0; m < 4; ++m) _Pragma("unroll") for (int k = 0; k < 2; ++k) dst[m][k] = *(const LAS bf16x8*)(lds + PG8_SA(b, h) + aoff + m * 2048 + k * KOFF); } while (0)
; #define PG8_WAIT_V(n) asm volatile("s_waitcnt vmcnt(" #n ")" ::: "memory")
; #define PG8_WAIT_L(n) asm volatile("s_waitcnt lgkmcnt(" #n ")" ::: "memory")
; #define PG8_BAR __builtin_amdgcn_s_barrier()
; #define PG8_SCHED __builtin_amdgcn_sched_barrier(0)
; template <class Epi, bool ALIGN_EPI = true, bool FP8 = false>
; __device__ __forceinline__ void gemm_phase(LAS unsigned char* lds, const Gemm g, const StaticOrder& S, const Epi& E, const int wid) {
;     ...
;             PG8_LDA(At, 1, 1); PG8_STAGE(PG8_SB(1, 0), b3, voffB); PG8_STAGE(PG8_SB(1, 1), b3 + hstep, voffB); PG8_STAGE(PG8_SA(1, 0), a3, voffA);
;             PG8_WAIT_V(8); PG8_WAIT_L(0); PG8_BAR; PG8_MMA(1, 0, At, B0); PG8_MMA(1, 1, At, B1); PG8_BAR; PG8_SCHED;
;         }
	s_setprio 0
	s_add_i32 s36, s54, s48
	v_lshl_add_u64 v[214:215], v[214:215], 0, s[16:17]
	s_mov_b32 m0, s36
	ds_read_b128 v[182:185], v153 offset:49152
	ds_read_b128 v[186:189], v153 offset:50176
	ds_read_b128 v[190:193], v153 offset:51200
	ds_read_b128 v[194:197], v153 offset:52224
	ds_read_b128 v[198:201], v153 offset:53248
	ds_read_b128 v[202:205], v153 offset:54272
	ds_read_b128 v[206:209], v153 offset:55296
	ds_read_b128 v[210:213], v153 offset:56320
	global_load_lds_dwordx4 v[214:215], off
	s_add_i32 m0, s36, 0x2000
	s_add_u32 s34, s34, 0x80080
	v_lshl_add_u64 v[214:215], v[216:217], 0, s[16:17]
	s_addc_u32 s35, s35, 0
	s_add_i32 s36, s64, s48
	global_load_lds_dwordx4 v[214:215], off
	v_lshl_add_u64 v[214:215], s[34:35], 0, v[132:133]
	s_mov_b32 m0, s36
	s_nop 0
	global_load_lds_dwordx4 v[214:215], off
	v_lshl_add_u64 v[214:215], s[34:35], 0, v[128:129]
	s_add_i32 m0, s36, 0x2000
	s_nop 0
	global_load_lds_dwordx4 v[214:215], off
	v_lshl_add_u64 v[214:215], v[218:219], 0, s[16:17]
	s_mov_b32 m0, s83
	s_nop 0
	global_load_lds_dwordx4 v[214:215], off
	v_lshl_add_u64 v[214:215], v[220:221], 0, s[16:17]
	s_mov_b32 m0, s84
	s_nop 0
	global_load_lds_dwordx4 v[214:215], off
	s_setprio 1
	s_waitcnt vmcnt(8) lgkmcnt(0)
	s_barrier
	v_mfma_f32_16x16x32_bf16 v[60:63], v[146:149], v[182:185], v[60:63]
	v_mfma_f32_16x16x32_bf16 v[56:59], v[158:161], v[182:185], v[56:59]
	v_mfma_f32_16x16x32_bf16 v[40:43], v[158:161], v[190:193], v[40:43]
	v_mfma_f32_16x16x32_bf16 v[44:47], v[146:149], v[190:193], v[44:47]
	v_mfma_f32_16x16x32_bf16 v[28:31], v[146:149], v[198:201], v[28:31]
	v_mfma_f32_16x16x32_bf16 v[24:27], v[158:161], v[198:201], v[24:27]
	v_mfma_f32_16x16x32_bf16 v[8:11], v[158:161], v[206:209], v[8:11]
	v_mfma_f32_16x16x32_bf16 v[12:15], v[146:149], v[206:209], v[12:15]
	v_mfma_f32_16x16x32_bf16 v[60:63], v[154:157], v[186:189], v[60:63]
	v_mfma_f32_16x16x32_bf16 v[56:59], v[162:165], v[186:189], v[56:59]
	v_mfma_f32_16x16x32_bf16 v[40:43], v[162:165], v[194:197], v[40:43]
	v_mfma_f32_16x16x32_bf16 v[44:47], v[154:157], v[194:197], v[44:47]
	v_mfma_f32_16x16x32_bf16 v[28:31], v[154:157], v[202:205], v[28:31]
	v_mfma_f32_16x16x32_bf16 v[24:27], v[162:165], v[202:205], v[24:27]
	v_mfma_f32_16x16x32_bf16 v[8:11], v[162:165], v[210:213], v[8:11]
	v_mfma_f32_16x16x32_bf16 v[12:15], v[154:157], v[210:213], v[12:15]
	v_mfma_f32_16x16x32_bf16 v[52:55], v[166:169], v[182:185], v[52:55]
	v_mfma_f32_16x16x32_bf16 v[48:51], v[174:177], v[182:185], v[48:51]
	v_mfma_f32_16x16x32_bf16 v[32:35], v[174:177], v[190:193], v[32:35]
	v_mfma_f32_16x16x32_bf16 v[36:39], v[166:169], v[190:193], v[36:39]
	v_mfma_f32_16x16x32_bf16 v[20:23], v[166:169], v[198:201], v[20:23]
	v_mfma_f32_16x16x32_bf16 v[16:19], v[174:177], v[198:201], v[16:19]
	v_mfma_f32_16x16x32_bf16 v[0:3], v[174:177], v[206:209], v[0:3]
	v_mfma_f32_16x16x32_bf16 v[4:7], v[166:169], v[206:209], v[4:7]
	v_mfma_f32_16x16x32_bf16 v[52:55], v[170:173], v[186:189], v[52:55]
	v_mfma_f32_16x16x32_bf16 v[48:51], v[178:181], v[186:189], v[48:51]
	v_mfma_f32_16x16x32_bf16 v[32:35], v[178:181], v[194:197], v[32:35]
	v_mfma_f32_16x16x32_bf16 v[36:39], v[170:173], v[194:197], v[36:39]
	v_mfma_f32_16x16x32_bf16 v[20:23], v[170:173], v[202:205], v[20:23]
	v_mfma_f32_16x16x32_bf16 v[16:19], v[178:181], v[202:205], v[16:19]
	v_mfma_f32_16x16x32_bf16 v[0:3], v[178:181], v[210:213], v[0:3]
	v_mfma_f32_16x16x32_bf16 v[4:7], v[170:173], v[210:213], v[4:7]
	s_barrier
	s_setprio 0
	s_add_u32 s30, s30, 0x100
	s_addc_u32 s31, s31, 0
	s_add_u32 s42, s42, 0x100
	s_addc_u32 s43, s43, 0
	s_cmp_ge_u32 s52, s9
	s_mov_b32 s34, s52
	s_cbranch_scc0 .LBB0_506
	s_and_b64 vcc, exec, s[12:13]
	s_cbranch_vccz .LBB0_509

; #define PG8_STAGE(bufoff, gbase, voff) do { _Pragma("unroll") for (int _i = 0; _i < 2; ++_i) \
;         __builtin_amdgcn_global_load_lds((const unsigned*)((const char*)(gbase) + (voff)[_i]), (LAS unsigned*)(lds + (bufoff) + ldsw + _i * 8192), 16, 0, 0); } while (0)
; #define PG8_LDA(dst, b, h) do { _Pragma("unroll") for (int m = 0; m < 4; ++m) _Pragma("unroll") for (int k = 0; k < 2; ++k) dst[m][k] = *(const LAS bf16x8*)(lds + PG8_SA(b, h) + aoff + m * 2048 + k * KOFF); } while (0)
; #define PG8_LDB(dst, b, h) do { _Pragma("unroll") for (int n = 0; n < 2; ++n) _Pragma("unroll") for (int k = 0; k < 2; ++k) dst[n][k] = *(const LAS bf16x8*)(lds + PG8_SB(b, h) + boff + n * 2048 + k * KOFF); } while (0)
; #define PG8_WAIT_V(n) asm volatile("s_waitcnt vmcnt(" #n ")" ::: "memory")
; #define PG8_WAIT_L(n) asm volatile("s_waitcnt lgkmcnt(" #n ")" ::: "memory")
; #define PG8_BAR __builtin_amdgcn_s_barrier()
; #define PG8_SCHED __builtin_amdgcn_sched_barrier(0)
; template <class Epi, bool ALIGN_EPI = true, bool FP8 = false>
; __device__ __forceinline__ void gemm_phase(LAS unsigned char* lds, const Gemm g, const StaticOrder& S, const Epi& E, const int wid) {
;     ...
;             const char* a1 = cA + (size_t)(t + 1) * kstep;
;             const char* a2 = last ? nA : cA + (size_t)(t + 2) * kstep; const char* b2 = last ? nB : cB + (size_t)(t + 2) * kstep;
;             const char* a3 = a2 + kstep; const char* b3 = b2 + kstep;
;             PG8_LDB(B0, 0, 0); PG8_LDB(B1, 0, 1); PG8_SCHED; PG8_LDA(At, 0, 0); PG8_STAGE(PG8_SA(1, 1), a1 + hstep, voffA);
;             PG8_WAIT_V(8); PG8_WAIT_L(0); PG8_BAR; PG8_MMA(0, 0, At, B0); PG8_MMA(0, 1, At, B1); PG8_BAR; PG8_SCHED;
;             PG8_LDA(At, 0, 1); PG8_STAGE(PG8_SB(0, 0), b2, voffB); PG8_STAGE(PG8_SB(0, 1), b2 + hstep, voffB); PG8_STAGE(PG8_SA(0, 0), a2, voffA);
;             PG8_WAIT_V(8); PG8_WAIT_L(0); PG8_BAR; PG8_MMA(1, 0, At, B0); PG8_MMA(1, 1, At, B1); PG8_BAR; PG8_SCHED;
.LBB0_2452:
	ds_read_b128 v[152:155], v148
	ds_read_b128 v[156:159], v148 offset:1024
	ds_read_b128 v[160:163], v148 offset:2048
	ds_read_b128 v[164:167], v148 offset:3072
	ds_read_b128 v[168:171], v149
	ds_read_b128 v[172:175], v149 offset:1024
	ds_read_b128 v[176:179], v149 offset:2048
	ds_read_b128 v[180:183], v149 offset:3072
	s_add_i32 s76, s30, 2
	s_add_u32 s31, s28, 0xfff80080
	s_addc_u32 s34, s29, -1
	s_cmp_eq_u32 s43, s30
	s_cselect_b32 s30, s42, s52
	s_cselect_b32 s35, s3, s34
	s_cselect_b32 s34, s17, s31
	s_cselect_b32 s31, s19, s75
	v_lshl_add_u64 v[144:145], s[28:29], 0, v[138:139]
	s_add_i32 m0, s25, 0xc000
	ds_read_b128 v[184:187], v150
	ds_read_b128 v[188:191], v150 offset:1024
	ds_read_b128 v[192:195], v150 offset:2048
	ds_read_b128 v[196:199], v150 offset:3072
	ds_read_b128 v[200:203], v150 offset:4096
	ds_read_b128 v[204:207], v150 offset:5120
	ds_read_b128 v[208:211], v150 offset:6144
	ds_read_b128 v[212:215], v150 offset:7168
	global_load_lds_dwordx4 v[144:145], off
	v_lshl_add_u64 v[144:145], s[28:29], 0, v[140:141]
	s_add_i32 m0, s25, 0xe000
	s_nop 0
	global_load_lds_dwordx4 v[144:145], off
	s_setprio 1
	s_waitcnt vmcnt(8) lgkmcnt(0)
	s_barrier
	v_mfma_f32_16x16x32_bf16 v[124:127], v[152:155], v[184:187], v[124:127]
	v_mfma_f32_16x16x32_bf16 v[116:119], v[160:163], v[184:187], v[116:119]
	v_mfma_f32_16x16x32_bf16 v[100:103], v[160:163], v[192:195], v[100:103]
	v_mfma_f32_16x16x32_bf16 v[108:111], v[152:155], v[192:195], v[108:111]
	v_mfma_f32_16x16x32_bf16 v[92:95], v[152:155], v[200:203], v[92:95]
	v_mfma_f32_16x16x32_bf16 v[84:87], v[160:163], v[200:203], v[84:87]
	v_mfma_f32_16x16x32_bf16 v[68:71], v[160:163], v[208:211], v[68:71]
	v_mfma_f32_16x16x32_bf16 v[76:79], v[152:155], v[208:211], v[76:79]
	v_mfma_f32_16x16x32_bf16 v[124:127], v[156:159], v[188:191], v[124:127]
	v_mfma_f32_16x16x32_bf16 v[116:119], v[164:167], v[188:191], v[116:119]
	v_mfma_f32_16x16x32_bf16 v[100:103], v[164:167], v[196:199], v[100:103]
	v_mfma_f32_16x16x32_bf16 v[108:111], v[156:159], v[196:199], v[108:111]
	v_mfma_f32_16x16x32_bf16 v[92:95], v[156:159], v[204:207], v[92:95]
	v_mfma_f32_16x16x32_bf16 v[84:87], v[164:167], v[204:207], v[84:87]
	v_mfma_f32_16x16x32_bf16 v[68:71], v[164:167], v[212:215], v[68:71]
	v_mfma_f32_16x16x32_bf16 v[76:79], v[156:159], v[212:215], v[76:79]
	v_mfma_f32_16x16x32_bf16 v[120:123], v[168:171], v[184:187], v[120:123]
	v_mfma_f32_16x16x32_bf16 v[112:115], v[176:179], v[184:187], v[112:115]
	v_mfma_f32_16x16x32_bf16 v[96:99], v[176:179], v[192:195], v[96:99]
	v_mfma_f32_16x16x32_bf16 v[104:107], v[168:171], v[192:195], v[104:107]
	v_mfma_f32_16x16x32_bf16 v[88:91], v[168:171], v[200:203], v[88:91]
	v_mfma_f32_16x16x32_bf16 v[80:83], v[176:179], v[200:203], v[80:83]
	v_mfma_f32_16x16x32_bf16 v[64:67], v[176:179], v[208:211], v[64:67]
	v_mfma_f32_16x16x32_bf16 v[72:75], v[168:171], v[208:211], v[72:75]
	v_mfma_f32_16x16x32_bf16 v[120:123], v[172:175], v[188:191], v[120:123]
	v_mfma_f32_16x16x32_bf16 v[112:115], v[180:183], v[188:191], v[112:115]
	v_mfma_f32_16x16x32_bf16 v[96:99], v[180:183], v[196:199], v[96:99]
	v_mfma_f32_16x16x32_bf16 v[104:107], v[172:175], v[196:199], v[104:107]
	v_mfma_f32_16x16x32_bf16 v[88:91], v[172:175], v[204:207], v[88:91]
	v_mfma_f32_16x16x32_bf16 v[80:83], v[180:183], v[204:207], v[80:83]
	v_mfma_f32_16x16x32_bf16 v[64:67], v[180:183], v[212:215], v[64:67]
	v_mfma_f32_16x16x32_bf16 v[72:75], v[172:175], v[212:215], v[72:75]
	s_barrier
	s_setprio 0
	s_add_i32 s77, s65, s38
	v_lshl_add_u64 v[144:145], s[30:31], 0, v[132:133]
	s_mov_b32 m0, s77
	ds_read_b128 v[184:187], v150 offset:16384
	ds_read_b128 v[188:191], v150 offset:17408
	ds_read_b128 v[192:195], v150 offset:18432
	ds_read_b128 v[196:199], v150 offset:19456
	ds_read_b128 v[200:203], v150 offset:20480
	ds_read_b128 v[204:207], v150 offset:21504
	ds_read_b128 v[208:211], v150 offset:22528
	ds_read_b128 v[212:215], v150 offset:23552
	global_load_lds_dwordx4 v[144:145], off
	s_add_i32 m0, s77, 0x2000
	s_add_u32 s78, s30, 0x80000
	v_lshl_add_u64 v[216:217], s[30:31], 0, v[128:129]
	s_addc_u32 s79, s31, 0
	s_add_i32 s77, s66, s38
	global_load_lds_dwordx4 v[216:217], off
	v_lshl_add_u64 v[218:219], s[78:79], 0, v[132:133]
	s_mov_b32 m0, s77
	v_lshl_add_u64 v[220:221], s[34:35], 0, v[130:131]
	global_load_lds_dwordx4 v[218:219], off
	v_lshl_add_u64 v[218:219], s[78:79], 0, v[128:129]
	s_add_i32 m0, s77, 0x2000
	s_nop 0
	global_load_lds_dwordx4 v[218:219], off
	v_lshl_add_u64 v[218:219], s[34:35], 0, v[134:135]
	s_mov_b32 m0, s25
	s_nop 0
	global_load_lds_dwordx4 v[218:219], off
	s_mov_b32 m0, s27
	s_nop 0
	global_load_lds_dwordx4 v[220:221], off
	s_setprio 1
	s_waitcnt vmcnt(8) lgkmcnt(0)
	s_barrier
; #define PG8_STAGE(bufoff, gbase, voff) do { _Pragma("unroll") for (int _i = 0; _i < 2; ++_i) \
;         __builtin_amdgcn_global_load_lds((const unsigned*)((const char*)(gbase) + (voff)[_i]), (LAS unsigned*)(lds + (bufoff) + ldsw + _i * 8192), 16, 0, 0); } while (0)
; #define PG8_LDA(dst, b, h) do { _Pragma("unroll") for (int m = 0; m < 4; ++m) _Pragma("unroll") for (int k = 0; k < 2; ++k) dst[m][k] = *(const LAS bf16x8*)(lds + PG8_SA(b, h) + aoff + m * 2048 + k * KOFF); } while (0)
; #define PG8_LDB(dst, b, h) do { _Pragma("unroll") for (int n = 0; n < 2; ++n) _Pragma("unroll") for (int k = 0; k < 2; ++k) dst[n][k] = *(const LAS bf16x8*)(lds + PG8_SB(b, h) + boff + n * 2048 + k * KOFF); } while (0)
; #define PG8_WAIT_V(n) asm volatile("s_waitcnt vmcnt(" #n ")" ::: "memory")
; #define PG8_WAIT_L(n) asm volatile("s_waitcnt lgkmcnt(" #n ")" ::: "memory")
; #define PG8_BAR __builtin_amdgcn_s_barrier()
; #define PG8_SCHED __builtin_amdgcn_sched_barrier(0)
; template <class Epi, bool ALIGN_EPI = true, bool FP8 = false>
; __device__ __forceinline__ void gemm_phase(LAS unsigned char* lds, const Gemm g, const StaticOrder& S, const Epi& E, const int wid) {
;     ...
;             PG8_WAIT_V(8); PG8_WAIT_L(0); PG8_BAR; PG8_MMA(1, 0, At, B0); PG8_MMA(1, 1, At, B1); PG8_BAR; PG8_SCHED;
;             PG8_LDB(B0, 1, 0); PG8_LDB(B1, 1, 1); PG8_SCHED; PG8_LDA(At, 1, 0); PG8_STAGE(PG8_SA(0, 1), a2 + hstep, voffA);
;             PG8_WAIT_V(8); PG8_WAIT_L(0); PG8_BAR; PG8_MMA(0, 0, At, B0); PG8_MMA(0, 1, At, B1); PG8_BAR; PG8_SCHED;
	v_mfma_f32_16x16x32_bf16 v[60:63], v[152:155], v[184:187], v[60:63]
	v_mfma_f32_16x16x32_bf16 v[52:55], v[160:163], v[184:187], v[52:55]
	v_mfma_f32_16x16x32_bf16 v[36:39], v[160:163], v[192:195], v[36:39]
	v_mfma_f32_16x16x32_bf16 v[44:47], v[152:155], v[192:195], v[44:47]
	v_mfma_f32_16x16x32_bf16 v[28:31], v[152:155], v[200:203], v[28:31]
	v_mfma_f32_16x16x32_bf16 v[20:23], v[160:163], v[200:203], v[20:23]
	v_mfma_f32_16x16x32_bf16 v[4:7], v[160:163], v[208:211], v[4:7]
	v_mfma_f32_16x16x32_bf16 v[12:15], v[152:155], v[208:211], v[12:15]
	v_mfma_f32_16x16x32_bf16 v[60:63], v[156:159], v[188:191], v[60:63]
	v_mfma_f32_16x16x32_bf16 v[52:55], v[164:167], v[188:191], v[52:55]
	v_mfma_f32_16x16x32_bf16 v[36:39], v[164:167], v[196:199], v[36:39]
	v_mfma_f32_16x16x32_bf16 v[44:47], v[156:159], v[196:199], v[44:47]
	v_mfma_f32_16x16x32_bf16 v[28:31], v[156:159], v[204:207], v[28:31]
	v_mfma_f32_16x16x32_bf16 v[20:23], v[164:167], v[204:207], v[20:23]
	v_mfma_f32_16x16x32_bf16 v[4:7], v[164:167], v[212:215], v[4:7]
	v_mfma_f32_16x16x32_bf16 v[12:15], v[156:159], v[212:215], v[12:15]
	v_mfma_f32_16x16x32_bf16 v[56:59], v[168:171], v[184:187], v[56:59]
	v_mfma_f32_16x16x32_bf16 v[48:51], v[176:179], v[184:187], v[48:51]
	v_mfma_f32_16x16x32_bf16 v[32:35], v[176:179], v[192:195], v[32:35]
	v_mfma_f32_16x16x32_bf16 v[40:43], v[168:171], v[192:195], v[40:43]
	v_mfma_f32_16x16x32_bf16 v[24:27], v[168:171], v[200:203], v[24:27]
	v_mfma_f32_16x16x32_bf16 v[16:19], v[176:179], v[200:203], v[16:19]
	v_mfma_f32_16x16x32_bf16 v[0:3], v[176:179], v[208:211], v[0:3]
	v_mfma_f32_16x16x32_bf16 v[8:11], v[168:171], v[208:211], v[8:11]
	v_mfma_f32_16x16x32_bf16 v[56:59], v[172:175], v[188:191], v[56:59]
	v_mfma_f32_16x16x32_bf16 v[48:51], v[180:183], v[188:191], v[48:51]
	v_mfma_f32_16x16x32_bf16 v[32:35], v[180:183], v[196:199], v[32:35]
	v_mfma_f32_16x16x32_bf16 v[40:43], v[172:175], v[196:199], v[40:43]
	v_mfma_f32_16x16x32_bf16 v[24:27], v[172:175], v[204:207], v[24:27]
	v_mfma_f32_16x16x32_bf16 v[16:19], v[180:183], v[204:207], v[16:19]
	v_mfma_f32_16x16x32_bf16 v[0:3], v[180:183], v[212:215], v[0:3]
	v_mfma_f32_16x16x32_bf16 v[8:11], v[172:175], v[212:215], v[8:11]
	s_barrier
	s_setprio 0
	s_add_i32 s77, 0, 0x18000
	s_add_i32 s78, 0, 0x1c000
	v_add_u32_e32 v164, s77, v147
	v_add_u32_e32 v180, s78, v147
	ds_read_b128 v[152:155], v164
	ds_read_b128 v[156:159], v164 offset:1024
	ds_read_b128 v[160:163], v164 offset:2048
	ds_read_b128 v[164:167], v164 offset:3072
	ds_read_b128 v[168:171], v180
	ds_read_b128 v[172:175], v180 offset:1024
	ds_read_b128 v[176:179], v180 offset:2048
	ds_read_b128 v[180:183], v180 offset:3072
	s_add_u32 s34, s34, 0x80000
	s_addc_u32 s35, s35, 0
	s_mov_b32 m0, s39
	v_lshl_add_u64 v[222:223], s[34:35], 0, v[134:135]
	ds_read_b128 v[184:187], v150 offset:32768
	ds_read_b128 v[188:191], v150 offset:33792
	ds_read_b128 v[192:195], v150 offset:34816
	ds_read_b128 v[196:199], v150 offset:35840
	ds_read_b128 v[200:203], v150 offset:36864
	ds_read_b128 v[204:207], v150 offset:37888
	ds_read_b128 v[208:211], v150 offset:38912
	ds_read_b128 v[212:215], v150 offset:39936
	global_load_lds_dwordx4 v[222:223], off
	v_lshl_add_u64 v[222:223], s[34:35], 0, v[130:131]
	s_mov_b32 m0, s48
	s_nop 0
	global_load_lds_dwordx4 v[222:223], off
	s_setprio 1
	s_waitcnt vmcnt(8) lgkmcnt(0)
	s_barrier
	v_mfma_f32_16x16x32_bf16 v[124:127], v[152:155], v[184:187], v[124:127]
	v_mfma_f32_16x16x32_bf16 v[116:119], v[160:163], v[184:187], v[116:119]
	v_mfma_f32_16x16x32_bf16 v[100:103], v[160:163], v[192:195], v[100:103]
	v_mfma_f32_16x16x32_bf16 v[108:111], v[152:155], v[192:195], v[108:111]
	v_mfma_f32_16x16x32_bf16 v[92:95], v[152:155], v[200:203], v[92:95]
	v_mfma_f32_16x16x32_bf16 v[84:87], v[160:163], v[200:203], v[84:87]
	v_mfma_f32_16x16x32_bf16 v[68:71], v[160:163], v[208:211], v[68:71]
	v_mfma_f32_16x16x32_bf16 v[76:79], v[152:155], v[208:211], v[76:79]
	v_mfma_f32_16x16x32_bf16 v[124:127], v[156:159], v[188:191], v[124:127]
	v_mfma_f32_16x16x32_bf16 v[116:119], v[164:167], v[188:191], v[116:119]
	v_mfma_f32_16x16x32_bf16 v[100:103], v[164:167], v[196:199], v[100:103]
	v_mfma_f32_16x16x32_bf16 v[108:111], v[156:159], v[196:199], v[108:111]
	v_mfma_f32_16x16x32_bf16 v[92:95], v[156:159], v[204:207], v[92:95]
	v_mfma_f32_16x16x32_bf16 v[84:87], v[164:167], v[204:207], v[84:87]
	v_mfma_f32_16x16x32_bf16 v[68:71], v[164:167], v[212:215], v[68:71]
	v_mfma_f32_16x16x32_bf16 v[76:79], v[156:159], v[212:215], v[76:79]
	v_mfma_f32_16x16x32_bf16 v[120:123], v[168:171], v[184:187], v[120:123]
	v_mfma_f32_16x16x32_bf16 v[112:115], v[176:179], v[184:187], v[112:115]
	v_mfma_f32_16x16x32_bf16 v[96:99], v[176:179], v[192:195], v[96:99]
	v_mfma_f32_16x16x32_bf16 v[104:107], v[168:171], v[192:195], v[104:107]
	v_mfma_f32_16x16x32_bf16 v[88:91], v[168:171], v[200:203], v[88:91]
	v_mfma_f32_16x16x32_bf16 v[80:83], v[176:179], v[200:203], v[80:83]
	v_mfma_f32_16x16x32_bf16 v[64:67], v[176:179], v[208:211], v[64:67]
	v_mfma_f32_16x16x32_bf16 v[72:75], v[168:171], v[208:211], v[72:75]
	v_mfma_f32_16x16x32_bf16 v[120:123], v[172:175], v[188:191], v[120:123]
	v_mfma_f32_16x16x32_bf16 v[112:115], v[180:183], v[188:191], v[112:115]
	v_mfma_f32_16x16x32_bf16 v[96:99], v[180:183], v[196:199], v[96:99]
	v_mfma_f32_16x16x32_bf16 v[104:107], v[172:175], v[196:199], v[104:107]
	v_mfma_f32_16x16x32_bf16 v[88:91], v[172:175], v[204:207], v[88:91]
	v_mfma_f32_16x16x32_bf16 v[80:83], v[180:183], v[204:207], v[80:83]
	v_mfma_f32_16x16x32_bf16 v[64:67], v[180:183], v[212:215], v[64:67]
	v_mfma_f32_16x16x32_bf16 v[72:75], v[172:175], v[212:215], v[72:75]
	s_barrier
; #define PG8_STAGE(bufoff, gbase, voff) do { _Pragma("unroll") for (int _i = 0; _i < 2; ++_i) \
;         __builtin_amdgcn_global_load_lds((const unsigned*)((const char*)(gbase) + (voff)[_i]), (LAS unsigned*)(lds + (bufoff) + ldsw + _i * 8192), 16, 0, 0); } while (0)
; #define PG8_LDA(dst, b, h) do { _Pragma("unroll") for (int m = 0; m < 4; ++m) _Pragma("unroll") for (int k = 0; k < 2; ++k) dst[m][k] = *(const LAS bf16x8*)(lds + PG8_SA(b, h) + aoff + m * 2048 + k * KOFF); } while (0)
; #define PG8_WAIT_V(n) asm volatile("s_waitcnt vmcnt(" #n ")" ::: "memory")
; #define PG8_WAIT_L(n) asm volatile("s_waitcnt lgkmcnt(" #n ")" ::: "memory")
; #define PG8_BAR __builtin_amdgcn_s_barrier()
; #define PG8_SCHED __builtin_amdgcn_sched_barrier(0)
; template <class Epi, bool ALIGN_EPI = true, bool FP8 = false>
; __device__ __forceinline__ void gemm_phase(LAS unsigned char* lds, const Gemm g, const StaticOrder& S, const Epi& E, const int wid) {
;     ...
;             PG8_LDA(At, 1, 1); PG8_STAGE(PG8_SB(1, 0), b3, voffB); PG8_STAGE(PG8_SB(1, 1), b3 + hstep, voffB); PG8_STAGE(PG8_SA(1, 0), a3, voffA);
;             PG8_WAIT_V(8); PG8_WAIT_L(0); PG8_BAR; PG8_MMA(1, 0, At, B0); PG8_MMA(1, 1, At, B1); PG8_BAR; PG8_SCHED;
;         }
	s_setprio 0
	s_add_i32 s34, s77, s38
	v_lshl_add_u64 v[144:145], v[144:145], 0, s[14:15]
	s_mov_b32 m0, s34
	ds_read_b128 v[184:187], v150 offset:49152
	ds_read_b128 v[188:191], v150 offset:50176
	ds_read_b128 v[192:195], v150 offset:51200
	ds_read_b128 v[196:199], v150 offset:52224
	ds_read_b128 v[200:203], v150 offset:53248
	ds_read_b128 v[204:207], v150 offset:54272
	ds_read_b128 v[208:211], v150 offset:55296
	ds_read_b128 v[212:215], v150 offset:56320
	global_load_lds_dwordx4 v[144:145], off
	s_add_i32 m0, s34, 0x2000
	s_add_u32 s30, s30, 0x80080
	v_lshl_add_u64 v[144:145], v[216:217], 0, s[14:15]
	s_addc_u32 s31, s31, 0
	s_add_i32 s34, s78, s38
	global_load_lds_dwordx4 v[144:145], off
	v_lshl_add_u64 v[144:145], s[30:31], 0, v[132:133]
	s_mov_b32 m0, s34
	s_nop 0
	global_load_lds_dwordx4 v[144:145], off
	v_lshl_add_u64 v[144:145], s[30:31], 0, v[128:129]
	s_add_i32 m0, s34, 0x2000
	s_nop 0
	global_load_lds_dwordx4 v[144:145], off
	v_lshl_add_u64 v[144:145], v[218:219], 0, s[14:15]
	s_mov_b32 m0, s53
	s_nop 0
	global_load_lds_dwordx4 v[144:145], off
	v_lshl_add_u64 v[144:145], v[220:221], 0, s[14:15]
	s_mov_b32 m0, s55
	s_nop 0
	global_load_lds_dwordx4 v[144:145], off
	s_setprio 1
	s_waitcnt vmcnt(8) lgkmcnt(0)
	s_barrier
	v_mfma_f32_16x16x32_bf16 v[60:63], v[152:155], v[184:187], v[60:63]
	v_mfma_f32_16x16x32_bf16 v[52:55], v[160:163], v[184:187], v[52:55]
	v_mfma_f32_16x16x32_bf16 v[36:39], v[160:163], v[192:195], v[36:39]
	v_mfma_f32_16x16x32_bf16 v[44:47], v[152:155], v[192:195], v[44:47]
	v_mfma_f32_16x16x32_bf16 v[28:31], v[152:155], v[200:203], v[28:31]
	v_mfma_f32_16x16x32_bf16 v[20:23], v[160:163], v[200:203], v[20:23]
	v_mfma_f32_16x16x32_bf16 v[4:7], v[160:163], v[208:211], v[4:7]
	v_mfma_f32_16x16x32_bf16 v[12:15], v[152:155], v[208:211], v[12:15]
	v_mfma_f32_16x16x32_bf16 v[60:63], v[156:159], v[188:191], v[60:63]
	v_mfma_f32_16x16x32_bf16 v[52:55], v[164:167], v[188:191], v[52:55]
	v_mfma_f32_16x16x32_bf16 v[36:39], v[164:167], v[196:199], v[36:39]
	v_mfma_f32_16x16x32_bf16 v[44:47], v[156:159], v[196:199], v[44:47]
	v_mfma_f32_16x16x32_bf16 v[28:31], v[156:159], v[204:207], v[28:31]
	v_mfma_f32_16x16x32_bf16 v[20:23], v[164:167], v[204:207], v[20:23]
	v_mfma_f32_16x16x32_bf16 v[4:7], v[164:167], v[212:215], v[4:7]
	v_mfma_f32_16x16x32_bf16 v[12:15], v[156:159], v[212:215], v[12:15]
	v_mfma_f32_16x16x32_bf16 v[56:59], v[168:171], v[184:187], v[56:59]
	v_mfma_f32_16x16x32_bf16 v[48:51], v[176:179], v[184:187], v[48:51]
	v_mfma_f32_16x16x32_bf16 v[32:35], v[176:179], v[192:195], v[32:35]
	v_mfma_f32_16x16x32_bf16 v[40:43], v[168:171], v[192:195], v[40:43]
	v_mfma_f32_16x16x32_bf16 v[24:27], v[168:171], v[200:203], v[24:27]
	v_mfma_f32_16x16x32_bf16 v[16:19], v[176:179], v[200:203], v[16:19]
	v_mfma_f32_16x16x32_bf16 v[0:3], v[176:179], v[208:211], v[0:3]
	v_mfma_f32_16x16x32_bf16 v[8:11], v[168:171], v[208:211], v[8:11]
	v_mfma_f32_16x16x32_bf16 v[56:59], v[172:175], v[188:191], v[56:59]
	v_mfma_f32_16x16x32_bf16 v[48:51], v[180:183], v[188:191], v[48:51]
	v_mfma_f32_16x16x32_bf16 v[32:35], v[180:183], v[196:199], v[32:35]
	v_mfma_f32_16x16x32_bf16 v[40:43], v[172:175], v[196:199], v[40:43]
	v_mfma_f32_16x16x32_bf16 v[24:27], v[172:175], v[204:207], v[24:27]
	v_mfma_f32_16x16x32_bf16 v[16:19], v[180:183], v[204:207], v[16:19]
	v_mfma_f32_16x16x32_bf16 v[0:3], v[180:183], v[212:215], v[0:3]
	v_mfma_f32_16x16x32_bf16 v[8:11], v[172:175], v[212:215], v[8:11]
	s_barrier
	s_setprio 0
	s_add_u32 s28, s28, 0x100
	s_addc_u32 s29, s29, 0
	s_add_u32 s52, s52, 0x100
	s_addc_u32 s75, s75, 0
	s_cmp_ge_u32 s76, s54
	s_mov_b32 s30, s76
	s_cbranch_scc0 .LBB0_2452
	s_and_b64 vcc, exec, s[12:13]
	s_cbranch_vccz .LBB0_2455
